# speedup vs baseline: 1.0068x; 1.0025x over previous
.LBB0_1405:
	s_ashr_i32 s21, s20, 31
	s_lshl_b64 s[20:21], s[20:21], 19
	s_add_u32 s2, s28, s20
	s_addc_u32 s25, s29, s21
	s_lshl_b32 s40, s39, 8
	s_ashr_i32 s41, s40, 31
	s_lshl_b64 s[22:23], s[40:41], 1
	s_add_u32 s24, s2, s22
	s_addc_u32 s25, s25, s23
	s_add_u32 s2, s92, s20
	s_addc_u32 s20, s93, s21
	s_add_u32 s22, s2, s22
	s_addc_u32 s23, s20, s23
	v_readlane_b32 s20, v255, 15
	v_readlane_b32 s21, v255, 16
	s_load_dwordx2 s[20:21], s[20:21], 0x90
	v_lshlrev_b32_e32 v132, 2, v188
	v_lshl_add_u64 v[130:131], s[24:25], 0, v[196:197]
	v_lshlrev_b32_e32 v0, 1, v188
	v_lshl_add_u64 v[130:131], v[130:131], 0, v[0:1]
	s_waitcnt lgkmcnt(0)
	s_add_u32 s2, s20, s34
	s_addc_u32 s39, s21, 0
	s_lshl_b64 s[20:21], s[40:41], 2
	s_add_u32 s20, s2, s20
	s_addc_u32 s21, s39, s21
	v_and_b32_e32 v176, 63, v182
	v_and_b32_e32 v174, 0x300, v132
	v_lshl_add_u32 v174, v176, 2, v174
	global_load_dword v175, v174, s[20:21]
	v_lshrrev_b32_e32 v173, 6, v182
	v_lshlrev_b32_e32 v173, 9, v173
	v_add_u32_e32 v173, 0x10000, v173
	v_and_b32_e32 v172, 48, v132
	v_add_u32_e32 v172, v173, v172
	v_lshl_add_u32 v173, v176, 2, v173
	v_bfe_u32 v176, v182, 4, 1
	v_mul_u32_u24_e32 v176, 24, v176
	v_mov_b32_e32 v177, 0
	v_lshl_add_u64 v[170:171], v[130:131], 0, v[176:177]
	global_load_dwordx4 v[142:145], v[170:171], off
	global_load_dwordx4 v[146:149], v[170:171], off offset:64
	v_add_co_u32_e32 v170, vcc, 0x8000, v170
	s_nop 1
	v_addc_co_u32_e32 v171, vcc, 0, v171, vcc
	global_load_dwordx4 v[150:153], v[170:171], off
	global_load_dwordx4 v[154:157], v[170:171], off offset:64
	v_add_co_u32_e32 v170, vcc, 0x8000, v170
	s_nop 1
	v_addc_co_u32_e32 v171, vcc, 0, v171, vcc
	global_load_dwordx4 v[158:161], v[170:171], off
	global_load_dwordx4 v[162:165], v[170:171], off offset:64
	v_add_co_u32_e32 v170, vcc, 0x8000, v170
	s_nop 1
	v_addc_co_u32_e32 v171, vcc, 0, v171, vcc
	global_load_dwordx4 v[166:169], v[170:171], off
	s_waitcnt vmcnt(7)
	ds_write_b32 v173, v175
	s_waitcnt lgkmcnt(0)
	ds_read_b128 v[134:137], v172
	s_waitcnt vmcnt(6)
	v_permlane16_swap_b32_e32 v142, v144
	v_permlane16_swap_b32_e32 v143, v145
	v_mov_b64_e32 v[138:139], v[142:143]
	s_waitcnt lgkmcnt(0)
	v_add_f32_e32 v126, v126, v134
	v_add_f32_e32 v127, v127, v135
	v_mul_f32_e32 v126, 0xbfb8aa3b, v126
	v_mul_f32_e32 v127, 0xbfb8aa3b, v127
	v_exp_f32_e32 v126, v126
	v_exp_f32_e32 v127, v127
	v_lshlrev_b32_e32 v133, 16, v138
	v_and_b32_e32 v138, 0xffff0000, v138
	v_add_f32_e32 v126, 1.0, v126
	v_add_f32_e32 v127, 1.0, v127
	v_rcp_f32_e32 v126, v126
	v_rcp_f32_e32 v127, v127
	v_lshlrev_b32_e32 v140, 16, v139
	v_and_b32_e32 v139, 0xffff0000, v139
	v_mul_f32_e32 v126, v126, v133
	v_mul_f32_e32 v127, v127, v138
	v_cvt_pk_bf16_f32 v248, v126, v127
	v_add_f32_e32 v126, v128, v136
	v_add_f32_e32 v127, v129, v137
	v_mul_f32_e32 v126, 0xbfb8aa3b, v126
	v_mul_f32_e32 v127, 0xbfb8aa3b, v127
	v_exp_f32_e32 v126, v126
	v_exp_f32_e32 v127, v127
	v_add_f32_e32 v126, 1.0, v126
	v_add_f32_e32 v127, 1.0, v127
	v_rcp_f32_e32 v126, v126
	v_rcp_f32_e32 v127, v127
	v_mul_f32_e32 v126, v126, v140
	v_mul_f32_e32 v127, v127, v139
	v_cvt_pk_bf16_f32 v249, v126, v127
	v_lshl_add_u64 v[126:127], s[22:23], 0, v[196:197]
	v_lshl_add_u64 v[126:127], v[126:127], 0, v[0:1]
	s_waitcnt vmcnt(6)
	v_mov_b64_e32 v[128:129], v[144:145]
	global_load_dwordx4 v[142:145], v[170:171], off offset:64
	v_add_co_u32_e32 v170, vcc, 0x8000, v170
	s_nop 1
	v_addc_co_u32_e32 v171, vcc, 0, v171, vcc
	ds_read_b128 v[134:137], v172 offset:64
	v_lshlrev_b32_e32 v133, 16, v128
	s_waitcnt lgkmcnt(0)
	v_add_f32_e32 v122, v122, v134
	v_add_f32_e32 v123, v123, v135
	v_mul_f32_e32 v122, 0xbfb8aa3b, v122
	v_mul_f32_e32 v123, 0xbfb8aa3b, v123
	v_exp_f32_e32 v122, v122
	v_exp_f32_e32 v123, v123
	v_and_b32_e32 v128, 0xffff0000, v128
	v_lshlrev_b32_e32 v138, 16, v129
	v_add_f32_e32 v122, 1.0, v122
	v_add_f32_e32 v123, 1.0, v123
	v_rcp_f32_e32 v122, v122
	v_rcp_f32_e32 v123, v123
	v_and_b32_e32 v129, 0xffff0000, v129
	v_mul_f32_e32 v122, v122, v133
	v_mul_f32_e32 v123, v123, v128
	v_cvt_pk_bf16_f32 v250, v122, v123
	v_add_f32_e32 v123, v124, v136
	v_mul_f32_e32 v123, 0xbfb8aa3b, v123
	v_add_f32_e32 v124, v125, v137
	v_exp_f32_e32 v123, v123
	v_mul_f32_e32 v124, 0xbfb8aa3b, v124
	v_exp_f32_e32 v124, v124
	v_add_f32_e32 v123, 1.0, v123
	v_rcp_f32_e32 v123, v123
	v_add_f32_e32 v124, 1.0, v124
	v_rcp_f32_e32 v124, v124
	v_mul_f32_e32 v123, v123, v138
	v_mul_f32_e32 v124, v124, v129
	v_cvt_pk_bf16_f32 v251, v123, v124
	v_lshl_add_u64 v[252:253], v[126:127], 0, v[176:177]
	s_nop 1
	v_permlane16_swap_b32_e32 v248, v250
	v_permlane16_swap_b32_e32 v249, v251
	global_store_dwordx4 v[252:253], v[248:251], off
	s_waitcnt vmcnt(7)
	v_permlane16_swap_b32_e32 v146, v148
	v_permlane16_swap_b32_e32 v147, v149
	v_mov_b64_e32 v[128:129], v[146:147]
	ds_read_b128 v[122:125], v172 offset:128
	v_lshlrev_b32_e32 v133, 16, v128
	s_waitcnt lgkmcnt(0)
	v_add_f32_e32 v118, v118, v122
	v_add_f32_e32 v119, v119, v123
	v_mul_f32_e32 v118, 0xbfb8aa3b, v118
	v_mul_f32_e32 v119, 0xbfb8aa3b, v119
	v_exp_f32_e32 v118, v118
	v_exp_f32_e32 v119, v119
	v_and_b32_e32 v128, 0xffff0000, v128
	v_lshlrev_b32_e32 v134, 16, v129
	v_add_f32_e32 v118, 1.0, v118
	v_add_f32_e32 v119, 1.0, v119
	v_rcp_f32_e32 v118, v118
	v_rcp_f32_e32 v119, v119
	v_and_b32_e32 v129, 0xffff0000, v129
	v_mul_f32_e32 v118, v118, v133
	v_mul_f32_e32 v119, v119, v128
	v_cvt_pk_bf16_f32 v248, v118, v119
	v_add_f32_e32 v119, v120, v124
	v_mul_f32_e32 v119, 0xbfb8aa3b, v119
	v_add_f32_e32 v120, v121, v125
	v_exp_f32_e32 v119, v119
	v_mul_f32_e32 v120, 0xbfb8aa3b, v120
	v_exp_f32_e32 v120, v120
	v_add_f32_e32 v119, 1.0, v119
	v_rcp_f32_e32 v119, v119
	v_add_f32_e32 v120, 1.0, v120
	v_rcp_f32_e32 v120, v120
	v_mul_f32_e32 v119, v119, v134
	v_mul_f32_e32 v120, v120, v129
	v_cvt_pk_bf16_f32 v249, v119, v120
	s_waitcnt vmcnt(7)
	v_mov_b64_e32 v[118:119], v[148:149]
	global_load_dwordx4 v[146:149], v[170:171], off
	ds_read_b128 v[120:123], v172 offset:192
	v_lshlrev_b32_e32 v124, 16, v118
	s_waitcnt lgkmcnt(0)
	v_add_f32_e32 v114, v114, v120
	v_add_f32_e32 v115, v115, v121
	v_mul_f32_e32 v114, 0xbfb8aa3b, v114
	v_mul_f32_e32 v115, 0xbfb8aa3b, v115
	v_exp_f32_e32 v114, v114
	v_exp_f32_e32 v115, v115
	v_and_b32_e32 v118, 0xffff0000, v118
	v_lshlrev_b32_e32 v125, 16, v119
	v_add_f32_e32 v114, 1.0, v114
	v_add_f32_e32 v115, 1.0, v115
	v_rcp_f32_e32 v114, v114
	v_rcp_f32_e32 v115, v115
	v_and_b32_e32 v119, 0xffff0000, v119
	v_mul_f32_e32 v114, v114, v124
	v_mul_f32_e32 v115, v115, v118
	v_cvt_pk_bf16_f32 v250, v114, v115
	v_add_f32_e32 v115, v116, v122
	v_mul_f32_e32 v115, 0xbfb8aa3b, v115
	v_add_f32_e32 v116, v117, v123
	v_exp_f32_e32 v115, v115
	v_mul_f32_e32 v116, 0xbfb8aa3b, v116
	v_exp_f32_e32 v116, v116
	v_add_f32_e32 v115, 1.0, v115
	v_rcp_f32_e32 v115, v115
	v_add_f32_e32 v116, 1.0, v116
	v_rcp_f32_e32 v116, v116
	v_mul_f32_e32 v115, v115, v125
	v_mul_f32_e32 v116, v116, v119
	v_cvt_pk_bf16_f32 v251, v115, v116
	v_lshl_add_u64 v[252:253], v[126:127], 0, v[176:177]
	s_nop 1
	v_permlane16_swap_b32_e32 v248, v250
	v_permlane16_swap_b32_e32 v249, v251
	global_store_dwordx4 v[252:253], v[248:251], off offset:64
	v_lshl_add_u64 v[114:115], s[24:25], 0, v[198:199]
	v_lshl_add_u64 v[114:115], v[114:115], 0, v[0:1]
	s_waitcnt vmcnt(8)
	v_permlane16_swap_b32_e32 v150, v152
	v_permlane16_swap_b32_e32 v151, v153
	v_mov_b64_e32 v[120:121], v[150:151]
	ds_read_b128 v[116:119], v172
	v_lshlrev_b32_e32 v122, 16, v120
	s_waitcnt lgkmcnt(0)
	v_add_f32_e32 v110, v110, v116
	v_add_f32_e32 v111, v111, v117
	v_mul_f32_e32 v110, 0xbfb8aa3b, v110
	v_mul_f32_e32 v111, 0xbfb8aa3b, v111
	v_exp_f32_e32 v110, v110
	v_exp_f32_e32 v111, v111
	v_and_b32_e32 v120, 0xffff0000, v120
	v_lshlrev_b32_e32 v123, 16, v121
	v_add_f32_e32 v110, 1.0, v110
	v_add_f32_e32 v111, 1.0, v111
	v_rcp_f32_e32 v110, v110
	v_rcp_f32_e32 v111, v111
	v_and_b32_e32 v121, 0xffff0000, v121
	v_mul_f32_e32 v110, v110, v122
	v_mul_f32_e32 v111, v111, v120
	v_cvt_pk_bf16_f32 v248, v110, v111
	v_add_f32_e32 v110, v112, v118
	v_add_f32_e32 v111, v113, v119
	v_mul_f32_e32 v110, 0xbfb8aa3b, v110
	v_mul_f32_e32 v111, 0xbfb8aa3b, v111
	v_exp_f32_e32 v110, v110
	v_exp_f32_e32 v111, v111
	v_add_f32_e32 v110, 1.0, v110
	v_add_f32_e32 v111, 1.0, v111
	v_rcp_f32_e32 v110, v110
	v_rcp_f32_e32 v111, v111
	v_mul_f32_e32 v110, v110, v123
	v_mul_f32_e32 v111, v111, v121
	v_cvt_pk_bf16_f32 v249, v110, v111
	v_lshl_add_u64 v[110:111], s[22:23], 0, v[198:199]
	v_lshl_add_u64 v[110:111], v[110:111], 0, v[0:1]
	s_waitcnt vmcnt(8)
	v_mov_b64_e32 v[112:113], v[152:153]
	global_load_dwordx4 v[150:153], v[170:171], off offset:64
	v_add_co_u32_e32 v170, vcc, 0x8000, v170
	s_nop 1
	v_addc_co_u32_e32 v171, vcc, 0, v171, vcc
	ds_read_b128 v[116:119], v172 offset:64
	v_lshlrev_b32_e32 v120, 16, v112
	s_waitcnt lgkmcnt(0)
	v_add_f32_e32 v106, v106, v116
	v_add_f32_e32 v107, v107, v117
	v_mul_f32_e32 v106, 0xbfb8aa3b, v106
	v_mul_f32_e32 v107, 0xbfb8aa3b, v107
	v_exp_f32_e32 v106, v106
	v_exp_f32_e32 v107, v107
	v_and_b32_e32 v112, 0xffff0000, v112
	v_lshlrev_b32_e32 v121, 16, v113
	v_add_f32_e32 v106, 1.0, v106
	v_add_f32_e32 v107, 1.0, v107
	v_rcp_f32_e32 v106, v106
	v_rcp_f32_e32 v107, v107
	v_and_b32_e32 v113, 0xffff0000, v113
	v_mul_f32_e32 v106, v106, v120
	v_mul_f32_e32 v107, v107, v112
	v_cvt_pk_bf16_f32 v250, v106, v107
	v_add_f32_e32 v107, v108, v118
	v_mul_f32_e32 v107, 0xbfb8aa3b, v107
	v_add_f32_e32 v108, v109, v119
	v_exp_f32_e32 v107, v107
	v_mul_f32_e32 v108, 0xbfb8aa3b, v108
	v_exp_f32_e32 v108, v108
	v_add_f32_e32 v107, 1.0, v107
	v_rcp_f32_e32 v107, v107
	v_add_f32_e32 v108, 1.0, v108
	v_rcp_f32_e32 v108, v108
	v_mul_f32_e32 v107, v107, v121
	v_mul_f32_e32 v108, v108, v113
	v_cvt_pk_bf16_f32 v251, v107, v108
	v_lshl_add_u64 v[252:253], v[110:111], 0, v[176:177]
	s_nop 1
	v_permlane16_swap_b32_e32 v248, v250
	v_permlane16_swap_b32_e32 v249, v251
	global_store_dwordx4 v[252:253], v[248:251], off
	s_waitcnt vmcnt(9)
	v_permlane16_swap_b32_e32 v154, v156
	v_permlane16_swap_b32_e32 v155, v157
	v_mov_b64_e32 v[112:113], v[154:155]
	ds_read_b128 v[106:109], v172 offset:128
	v_lshlrev_b32_e32 v116, 16, v112
	s_waitcnt lgkmcnt(0)
	v_add_f32_e32 v102, v102, v106
	v_add_f32_e32 v103, v103, v107
	v_mul_f32_e32 v102, 0xbfb8aa3b, v102
	v_mul_f32_e32 v103, 0xbfb8aa3b, v103
	v_exp_f32_e32 v102, v102
	v_exp_f32_e32 v103, v103
	v_and_b32_e32 v112, 0xffff0000, v112
	v_lshlrev_b32_e32 v117, 16, v113
	v_add_f32_e32 v102, 1.0, v102
	v_add_f32_e32 v103, 1.0, v103
	v_rcp_f32_e32 v102, v102
	v_rcp_f32_e32 v103, v103
	v_and_b32_e32 v113, 0xffff0000, v113
	v_mul_f32_e32 v102, v102, v116
	v_mul_f32_e32 v103, v103, v112
	v_cvt_pk_bf16_f32 v248, v102, v103
	v_add_f32_e32 v103, v104, v108
	v_mul_f32_e32 v103, 0xbfb8aa3b, v103
	v_add_f32_e32 v104, v105, v109
	v_exp_f32_e32 v103, v103
	v_mul_f32_e32 v104, 0xbfb8aa3b, v104
	v_exp_f32_e32 v104, v104
	v_add_f32_e32 v103, 1.0, v103
	v_rcp_f32_e32 v103, v103
	v_add_f32_e32 v104, 1.0, v104
	v_rcp_f32_e32 v104, v104
	v_mul_f32_e32 v103, v103, v117
	v_mul_f32_e32 v104, v104, v113
	v_cvt_pk_bf16_f32 v249, v103, v104
	s_waitcnt vmcnt(9)
	v_mov_b64_e32 v[102:103], v[156:157]
	global_load_dwordx4 v[154:157], v[170:171], off
	ds_read_b128 v[104:107], v172 offset:192
	v_lshlrev_b32_e32 v108, 16, v102
	s_waitcnt lgkmcnt(0)
	v_add_f32_e32 v98, v98, v104
	v_add_f32_e32 v99, v99, v105
	v_mul_f32_e32 v98, 0xbfb8aa3b, v98
	v_mul_f32_e32 v99, 0xbfb8aa3b, v99
	v_exp_f32_e32 v98, v98
	v_exp_f32_e32 v99, v99
	v_and_b32_e32 v102, 0xffff0000, v102
	v_lshlrev_b32_e32 v109, 16, v103
	v_add_f32_e32 v98, 1.0, v98
	v_add_f32_e32 v99, 1.0, v99
	v_rcp_f32_e32 v98, v98
	v_rcp_f32_e32 v99, v99
	v_and_b32_e32 v103, 0xffff0000, v103
	v_mul_f32_e32 v98, v98, v108
	v_mul_f32_e32 v99, v99, v102
	v_cvt_pk_bf16_f32 v250, v98, v99
	v_add_f32_e32 v99, v100, v106
	v_mul_f32_e32 v99, 0xbfb8aa3b, v99
	v_add_f32_e32 v100, v101, v107
	v_exp_f32_e32 v99, v99
	v_mul_f32_e32 v100, 0xbfb8aa3b, v100
	v_exp_f32_e32 v100, v100
	v_add_f32_e32 v99, 1.0, v99
	v_rcp_f32_e32 v99, v99
	v_add_f32_e32 v100, 1.0, v100
	v_rcp_f32_e32 v100, v100
	v_mul_f32_e32 v99, v99, v109
	v_mul_f32_e32 v100, v100, v103
	v_cvt_pk_bf16_f32 v251, v99, v100
	v_lshl_add_u64 v[252:253], v[110:111], 0, v[176:177]
	s_nop 1
	v_permlane16_swap_b32_e32 v248, v250
	v_permlane16_swap_b32_e32 v249, v251
	global_store_dwordx4 v[252:253], v[248:251], off offset:64
	v_lshl_add_u64 v[98:99], s[24:25], 0, v[200:201]
	v_lshl_add_u64 v[98:99], v[98:99], 0, v[0:1]
	s_waitcnt vmcnt(10)
	v_permlane16_swap_b32_e32 v158, v160
	v_permlane16_swap_b32_e32 v159, v161
	v_mov_b64_e32 v[104:105], v[158:159]
	ds_read_b128 v[100:103], v172
	v_lshlrev_b32_e32 v106, 16, v104
	s_waitcnt lgkmcnt(0)
	v_add_f32_e32 v94, v94, v100
	v_add_f32_e32 v95, v95, v101
	v_mul_f32_e32 v94, 0xbfb8aa3b, v94
	v_mul_f32_e32 v95, 0xbfb8aa3b, v95
	v_exp_f32_e32 v94, v94
	v_exp_f32_e32 v95, v95
	v_and_b32_e32 v104, 0xffff0000, v104
	v_lshlrev_b32_e32 v107, 16, v105
	v_add_f32_e32 v94, 1.0, v94
	v_add_f32_e32 v95, 1.0, v95
	v_rcp_f32_e32 v94, v94
	v_rcp_f32_e32 v95, v95
	v_and_b32_e32 v105, 0xffff0000, v105
	v_mul_f32_e32 v94, v94, v106
	v_mul_f32_e32 v95, v95, v104
	v_cvt_pk_bf16_f32 v248, v94, v95
	v_add_f32_e32 v94, v96, v102
	v_add_f32_e32 v95, v97, v103
	v_mul_f32_e32 v94, 0xbfb8aa3b, v94
	v_mul_f32_e32 v95, 0xbfb8aa3b, v95
	v_exp_f32_e32 v94, v94
	v_exp_f32_e32 v95, v95
	v_add_f32_e32 v94, 1.0, v94
	v_add_f32_e32 v95, 1.0, v95
	v_rcp_f32_e32 v94, v94
	v_rcp_f32_e32 v95, v95
	v_mul_f32_e32 v94, v94, v107
	v_mul_f32_e32 v95, v95, v105
	v_cvt_pk_bf16_f32 v249, v94, v95
	v_lshl_add_u64 v[94:95], s[22:23], 0, v[200:201]
	v_lshl_add_u64 v[94:95], v[94:95], 0, v[0:1]
	s_waitcnt vmcnt(10)
	v_mov_b64_e32 v[96:97], v[160:161]
	global_load_dwordx4 v[158:161], v[170:171], off offset:64
	v_add_co_u32_e32 v170, vcc, 0x8000, v170
	s_nop 1
	v_addc_co_u32_e32 v171, vcc, 0, v171, vcc
	ds_read_b128 v[100:103], v172 offset:64
	v_lshlrev_b32_e32 v104, 16, v96
	s_waitcnt lgkmcnt(0)
	v_add_f32_e32 v90, v90, v100
	v_add_f32_e32 v91, v91, v101
	v_mul_f32_e32 v90, 0xbfb8aa3b, v90
	v_mul_f32_e32 v91, 0xbfb8aa3b, v91
	v_exp_f32_e32 v90, v90
	v_exp_f32_e32 v91, v91
	v_and_b32_e32 v96, 0xffff0000, v96
	v_lshlrev_b32_e32 v105, 16, v97
	v_add_f32_e32 v90, 1.0, v90
	v_add_f32_e32 v91, 1.0, v91
	v_rcp_f32_e32 v90, v90
	v_rcp_f32_e32 v91, v91
	v_and_b32_e32 v97, 0xffff0000, v97
	v_mul_f32_e32 v90, v90, v104
	v_mul_f32_e32 v91, v91, v96
	v_cvt_pk_bf16_f32 v250, v90, v91
	v_add_f32_e32 v91, v92, v102
	v_mul_f32_e32 v91, 0xbfb8aa3b, v91
	v_add_f32_e32 v92, v93, v103
	v_exp_f32_e32 v91, v91
	v_mul_f32_e32 v92, 0xbfb8aa3b, v92
	v_exp_f32_e32 v92, v92
	v_add_f32_e32 v91, 1.0, v91
	v_rcp_f32_e32 v91, v91
	v_add_f32_e32 v92, 1.0, v92
	v_rcp_f32_e32 v92, v92
	v_mul_f32_e32 v91, v91, v105
	v_mul_f32_e32 v92, v92, v97
	v_cvt_pk_bf16_f32 v251, v91, v92
	v_lshl_add_u64 v[252:253], v[94:95], 0, v[176:177]
	s_nop 1
	v_permlane16_swap_b32_e32 v248, v250
	v_permlane16_swap_b32_e32 v249, v251
	global_store_dwordx4 v[252:253], v[248:251], off
	s_waitcnt vmcnt(11)
	v_permlane16_swap_b32_e32 v162, v164
	v_permlane16_swap_b32_e32 v163, v165
	v_mov_b64_e32 v[96:97], v[162:163]
	ds_read_b128 v[90:93], v172 offset:128
	v_lshlrev_b32_e32 v100, 16, v96
	s_waitcnt lgkmcnt(0)
	v_add_f32_e32 v86, v86, v90
	v_add_f32_e32 v87, v87, v91
	v_mul_f32_e32 v86, 0xbfb8aa3b, v86
	v_mul_f32_e32 v87, 0xbfb8aa3b, v87
	v_exp_f32_e32 v86, v86
	v_exp_f32_e32 v87, v87
	v_and_b32_e32 v96, 0xffff0000, v96
	v_lshlrev_b32_e32 v101, 16, v97
	v_add_f32_e32 v86, 1.0, v86
	v_add_f32_e32 v87, 1.0, v87
	v_rcp_f32_e32 v86, v86
	v_rcp_f32_e32 v87, v87
	v_and_b32_e32 v97, 0xffff0000, v97
	v_mul_f32_e32 v86, v86, v100
	v_mul_f32_e32 v87, v87, v96
	v_cvt_pk_bf16_f32 v248, v86, v87
	v_add_f32_e32 v87, v88, v92
	v_mul_f32_e32 v87, 0xbfb8aa3b, v87
	v_add_f32_e32 v88, v89, v93
	v_exp_f32_e32 v87, v87
	v_mul_f32_e32 v88, 0xbfb8aa3b, v88
	v_exp_f32_e32 v88, v88
	v_add_f32_e32 v87, 1.0, v87
	v_rcp_f32_e32 v87, v87
	v_add_f32_e32 v88, 1.0, v88
	v_rcp_f32_e32 v88, v88
	v_mul_f32_e32 v87, v87, v101
	v_mul_f32_e32 v88, v88, v97
	v_cvt_pk_bf16_f32 v249, v87, v88
	s_waitcnt vmcnt(11)
	v_mov_b64_e32 v[86:87], v[164:165]
	global_load_dwordx4 v[162:165], v[170:171], off
	ds_read_b128 v[88:91], v172 offset:192
	v_lshlrev_b32_e32 v92, 16, v86
	s_waitcnt lgkmcnt(0)
	v_add_f32_e32 v82, v82, v88
	v_add_f32_e32 v83, v83, v89
	v_mul_f32_e32 v82, 0xbfb8aa3b, v82
	v_mul_f32_e32 v83, 0xbfb8aa3b, v83
	v_exp_f32_e32 v82, v82
	v_exp_f32_e32 v83, v83
	v_and_b32_e32 v86, 0xffff0000, v86
	v_lshlrev_b32_e32 v93, 16, v87
	v_add_f32_e32 v82, 1.0, v82
	v_add_f32_e32 v83, 1.0, v83
	v_rcp_f32_e32 v82, v82
	v_rcp_f32_e32 v83, v83
	v_and_b32_e32 v87, 0xffff0000, v87
	v_mul_f32_e32 v82, v82, v92
	v_mul_f32_e32 v83, v83, v86
	v_cvt_pk_bf16_f32 v250, v82, v83
	v_add_f32_e32 v83, v84, v90
	v_mul_f32_e32 v83, 0xbfb8aa3b, v83
	v_add_f32_e32 v84, v85, v91
	v_exp_f32_e32 v83, v83
	v_mul_f32_e32 v84, 0xbfb8aa3b, v84
	v_exp_f32_e32 v84, v84
	v_add_f32_e32 v83, 1.0, v83
	v_rcp_f32_e32 v83, v83
	v_add_f32_e32 v84, 1.0, v84
	v_rcp_f32_e32 v84, v84
	v_mul_f32_e32 v83, v83, v93
	v_mul_f32_e32 v84, v84, v87
	v_cvt_pk_bf16_f32 v251, v83, v84
	v_lshl_add_u64 v[252:253], v[94:95], 0, v[176:177]
	s_nop 1
	v_permlane16_swap_b32_e32 v248, v250
	v_permlane16_swap_b32_e32 v249, v251
	global_store_dwordx4 v[252:253], v[248:251], off offset:64
	v_lshl_add_u64 v[82:83], s[24:25], 0, v[202:203]
	v_lshl_add_u64 v[82:83], v[82:83], 0, v[0:1]
	s_waitcnt vmcnt(12)
	v_permlane16_swap_b32_e32 v166, v168
	v_permlane16_swap_b32_e32 v167, v169
	v_mov_b64_e32 v[88:89], v[166:167]
	ds_read_b128 v[84:87], v172
	v_lshlrev_b32_e32 v90, 16, v88
	s_waitcnt lgkmcnt(0)
	v_add_f32_e32 v78, v78, v84
	v_add_f32_e32 v79, v79, v85
	v_mul_f32_e32 v78, 0xbfb8aa3b, v78
	v_mul_f32_e32 v79, 0xbfb8aa3b, v79
	v_exp_f32_e32 v78, v78
	v_exp_f32_e32 v79, v79
	v_and_b32_e32 v88, 0xffff0000, v88
	v_lshlrev_b32_e32 v91, 16, v89
	v_add_f32_e32 v78, 1.0, v78
	v_add_f32_e32 v79, 1.0, v79
	v_rcp_f32_e32 v78, v78
	v_rcp_f32_e32 v79, v79
	v_and_b32_e32 v89, 0xffff0000, v89
	v_mul_f32_e32 v78, v78, v90
	v_mul_f32_e32 v79, v79, v88
	v_cvt_pk_bf16_f32 v248, v78, v79
	v_add_f32_e32 v78, v80, v86
	v_add_f32_e32 v79, v81, v87
	v_mul_f32_e32 v78, 0xbfb8aa3b, v78
	v_mul_f32_e32 v79, 0xbfb8aa3b, v79
	v_exp_f32_e32 v78, v78
	v_exp_f32_e32 v79, v79
	v_add_f32_e32 v78, 1.0, v78
	v_add_f32_e32 v79, 1.0, v79
	v_rcp_f32_e32 v78, v78
	v_rcp_f32_e32 v79, v79
	v_mul_f32_e32 v78, v78, v91
	v_mul_f32_e32 v79, v79, v89
	v_cvt_pk_bf16_f32 v249, v78, v79
	v_lshl_add_u64 v[78:79], s[22:23], 0, v[202:203]
	v_lshl_add_u64 v[78:79], v[78:79], 0, v[0:1]
	s_waitcnt vmcnt(12)
	v_mov_b64_e32 v[80:81], v[168:169]
	global_load_dwordx4 v[166:169], v[170:171], off offset:64
	v_add_co_u32_e32 v170, vcc, 0x8000, v170
	s_nop 1
	v_addc_co_u32_e32 v171, vcc, 0, v171, vcc
	ds_read_b128 v[84:87], v172 offset:64
	v_lshlrev_b32_e32 v88, 16, v80
	s_waitcnt lgkmcnt(0)
	v_add_f32_e32 v74, v74, v84
	v_add_f32_e32 v75, v75, v85
	v_mul_f32_e32 v74, 0xbfb8aa3b, v74
	v_mul_f32_e32 v75, 0xbfb8aa3b, v75
	v_exp_f32_e32 v74, v74
	v_exp_f32_e32 v75, v75
	v_and_b32_e32 v80, 0xffff0000, v80
	v_lshlrev_b32_e32 v89, 16, v81
	v_add_f32_e32 v74, 1.0, v74
	v_add_f32_e32 v75, 1.0, v75
	v_rcp_f32_e32 v74, v74
	v_rcp_f32_e32 v75, v75
	v_and_b32_e32 v81, 0xffff0000, v81
	v_mul_f32_e32 v74, v74, v88
	v_mul_f32_e32 v75, v75, v80
	v_cvt_pk_bf16_f32 v250, v74, v75
	v_add_f32_e32 v75, v76, v86
	v_mul_f32_e32 v75, 0xbfb8aa3b, v75
	v_add_f32_e32 v76, v77, v87
	v_exp_f32_e32 v75, v75
	v_mul_f32_e32 v76, 0xbfb8aa3b, v76
	v_exp_f32_e32 v76, v76
	v_add_f32_e32 v75, 1.0, v75
	v_rcp_f32_e32 v75, v75
	v_add_f32_e32 v76, 1.0, v76
	v_rcp_f32_e32 v76, v76
	v_mul_f32_e32 v75, v75, v89
	v_mul_f32_e32 v76, v76, v81
	v_cvt_pk_bf16_f32 v251, v75, v76
	v_lshl_add_u64 v[252:253], v[78:79], 0, v[176:177]
	s_nop 1
	v_permlane16_swap_b32_e32 v248, v250
	v_permlane16_swap_b32_e32 v249, v251
	global_store_dwordx4 v[252:253], v[248:251], off
	s_waitcnt vmcnt(13)
	v_permlane16_swap_b32_e32 v142, v144
	v_permlane16_swap_b32_e32 v143, v145
	v_mov_b64_e32 v[80:81], v[142:143]
	ds_read_b128 v[74:77], v172 offset:128
	v_lshlrev_b32_e32 v84, 16, v80
	s_waitcnt lgkmcnt(0)
	v_add_f32_e32 v70, v70, v74
	v_add_f32_e32 v71, v71, v75
	v_mul_f32_e32 v70, 0xbfb8aa3b, v70
	v_mul_f32_e32 v71, 0xbfb8aa3b, v71
	v_exp_f32_e32 v70, v70
	v_exp_f32_e32 v71, v71
	v_and_b32_e32 v80, 0xffff0000, v80
	v_lshlrev_b32_e32 v85, 16, v81
	v_add_f32_e32 v70, 1.0, v70
	v_add_f32_e32 v71, 1.0, v71
	v_rcp_f32_e32 v70, v70
	v_rcp_f32_e32 v71, v71
	v_and_b32_e32 v81, 0xffff0000, v81
	v_mul_f32_e32 v70, v70, v84
	v_mul_f32_e32 v71, v71, v80
	v_cvt_pk_bf16_f32 v248, v70, v71
	v_add_f32_e32 v71, v72, v76
	v_mul_f32_e32 v71, 0xbfb8aa3b, v71
	v_add_f32_e32 v72, v73, v77
	v_exp_f32_e32 v71, v71
	v_mul_f32_e32 v72, 0xbfb8aa3b, v72
	v_exp_f32_e32 v72, v72
	v_add_f32_e32 v71, 1.0, v71
	v_rcp_f32_e32 v71, v71
	v_add_f32_e32 v72, 1.0, v72
	v_rcp_f32_e32 v72, v72
	v_mul_f32_e32 v71, v71, v85
	v_mul_f32_e32 v72, v72, v81
	v_cvt_pk_bf16_f32 v249, v71, v72
	s_waitcnt vmcnt(13)
	v_mov_b64_e32 v[70:71], v[144:145]
	global_load_dwordx4 v[142:145], v[170:171], off
	ds_read_b128 v[72:75], v172 offset:192
	v_lshlrev_b32_e32 v76, 16, v70
	s_waitcnt lgkmcnt(0)
	v_add_f32_e32 v66, v66, v72
	v_add_f32_e32 v67, v67, v73
	v_mul_f32_e32 v66, 0xbfb8aa3b, v66
	v_mul_f32_e32 v67, 0xbfb8aa3b, v67
	v_exp_f32_e32 v66, v66
	v_exp_f32_e32 v67, v67
	v_and_b32_e32 v70, 0xffff0000, v70
	v_lshlrev_b32_e32 v77, 16, v71
	v_add_f32_e32 v66, 1.0, v66
	v_add_f32_e32 v67, 1.0, v67
	v_rcp_f32_e32 v66, v66
	v_rcp_f32_e32 v67, v67
	v_and_b32_e32 v71, 0xffff0000, v71
	v_mul_f32_e32 v66, v66, v76
	v_mul_f32_e32 v67, v67, v70
	v_cvt_pk_bf16_f32 v250, v66, v67
	v_add_f32_e32 v67, v68, v74
	v_mul_f32_e32 v67, 0xbfb8aa3b, v67
	v_add_f32_e32 v68, v69, v75
	v_exp_f32_e32 v67, v67
	v_mul_f32_e32 v68, 0xbfb8aa3b, v68
	v_exp_f32_e32 v68, v68
	v_add_f32_e32 v67, 1.0, v67
	v_rcp_f32_e32 v67, v67
	v_add_f32_e32 v68, 1.0, v68
	v_rcp_f32_e32 v68, v68
	v_mul_f32_e32 v67, v67, v77
	v_mul_f32_e32 v68, v68, v71
	v_cvt_pk_bf16_f32 v251, v67, v68
	v_lshl_add_u64 v[252:253], v[78:79], 0, v[176:177]
	s_nop 1
	v_permlane16_swap_b32_e32 v248, v250
	v_permlane16_swap_b32_e32 v249, v251
	global_store_dwordx4 v[252:253], v[248:251], off offset:64
	v_lshl_add_u64 v[66:67], s[24:25], 0, v[204:205]
	v_lshl_add_u64 v[66:67], v[66:67], 0, v[0:1]
	s_waitcnt vmcnt(13)
	v_permlane16_swap_b32_e32 v146, v148
	v_permlane16_swap_b32_e32 v147, v149
	v_mov_b64_e32 v[72:73], v[146:147]
	ds_read_b128 v[68:71], v172
	v_lshlrev_b32_e32 v74, 16, v72
	s_waitcnt lgkmcnt(0)
	v_add_f32_e32 v62, v62, v68
	v_add_f32_e32 v63, v63, v69
	v_mul_f32_e32 v62, 0xbfb8aa3b, v62
	v_mul_f32_e32 v63, 0xbfb8aa3b, v63
	v_exp_f32_e32 v62, v62
	v_exp_f32_e32 v63, v63
	v_and_b32_e32 v72, 0xffff0000, v72
	v_lshlrev_b32_e32 v75, 16, v73
	v_add_f32_e32 v62, 1.0, v62
	v_add_f32_e32 v63, 1.0, v63
	v_rcp_f32_e32 v62, v62
	v_rcp_f32_e32 v63, v63
	v_and_b32_e32 v73, 0xffff0000, v73
	v_mul_f32_e32 v62, v62, v74
	v_mul_f32_e32 v63, v63, v72
	v_cvt_pk_bf16_f32 v248, v62, v63
	v_add_f32_e32 v62, v64, v70
	v_add_f32_e32 v63, v65, v71
	v_mul_f32_e32 v62, 0xbfb8aa3b, v62
	v_mul_f32_e32 v63, 0xbfb8aa3b, v63
	v_exp_f32_e32 v62, v62
	v_exp_f32_e32 v63, v63
	v_add_f32_e32 v62, 1.0, v62
	v_add_f32_e32 v63, 1.0, v63
	v_rcp_f32_e32 v62, v62
	v_rcp_f32_e32 v63, v63
	v_mul_f32_e32 v62, v62, v75
	v_mul_f32_e32 v63, v63, v73
	v_cvt_pk_bf16_f32 v249, v62, v63
	v_lshl_add_u64 v[62:63], s[22:23], 0, v[204:205]
	v_lshl_add_u64 v[62:63], v[62:63], 0, v[0:1]
	s_waitcnt vmcnt(13)
	v_mov_b64_e32 v[64:65], v[148:149]
	global_load_dwordx4 v[146:149], v[170:171], off offset:64
	ds_read_b128 v[68:71], v172 offset:64
	v_lshlrev_b32_e32 v72, 16, v64
	s_waitcnt lgkmcnt(0)
	v_add_f32_e32 v58, v58, v68
	v_add_f32_e32 v59, v59, v69
	v_mul_f32_e32 v58, 0xbfb8aa3b, v58
	v_mul_f32_e32 v59, 0xbfb8aa3b, v59
	v_exp_f32_e32 v58, v58
	v_exp_f32_e32 v59, v59
	v_and_b32_e32 v64, 0xffff0000, v64
	v_lshlrev_b32_e32 v73, 16, v65
	v_add_f32_e32 v58, 1.0, v58
	v_add_f32_e32 v59, 1.0, v59
	v_rcp_f32_e32 v58, v58
	v_rcp_f32_e32 v59, v59
	v_and_b32_e32 v65, 0xffff0000, v65
	v_mul_f32_e32 v58, v58, v72
	v_mul_f32_e32 v59, v59, v64
	v_cvt_pk_bf16_f32 v250, v58, v59
	v_add_f32_e32 v59, v60, v70
	v_mul_f32_e32 v59, 0xbfb8aa3b, v59
	v_add_f32_e32 v60, v61, v71
	v_exp_f32_e32 v59, v59
	v_mul_f32_e32 v60, 0xbfb8aa3b, v60
	v_exp_f32_e32 v60, v60
	v_add_f32_e32 v59, 1.0, v59
	v_rcp_f32_e32 v59, v59
	v_add_f32_e32 v60, 1.0, v60
	v_rcp_f32_e32 v60, v60
	v_mul_f32_e32 v59, v59, v73
	v_mul_f32_e32 v60, v60, v65
	v_cvt_pk_bf16_f32 v251, v59, v60
	v_lshl_add_u64 v[252:253], v[62:63], 0, v[176:177]
	s_nop 1
	v_permlane16_swap_b32_e32 v248, v250
	v_permlane16_swap_b32_e32 v249, v251
	global_store_dwordx4 v[252:253], v[248:251], off
	s_waitcnt vmcnt(13)
	v_permlane16_swap_b32_e32 v150, v152
	v_permlane16_swap_b32_e32 v151, v153
	v_mov_b64_e32 v[64:65], v[150:151]
	ds_read_b128 v[58:61], v172 offset:128
	v_lshlrev_b32_e32 v68, 16, v64
	s_waitcnt lgkmcnt(0)
	v_add_f32_e32 v54, v54, v58
	v_add_f32_e32 v55, v55, v59
	v_mul_f32_e32 v54, 0xbfb8aa3b, v54
	v_mul_f32_e32 v55, 0xbfb8aa3b, v55
	v_exp_f32_e32 v54, v54
	v_exp_f32_e32 v55, v55
	v_and_b32_e32 v64, 0xffff0000, v64
	v_lshlrev_b32_e32 v69, 16, v65
	v_add_f32_e32 v54, 1.0, v54
	v_add_f32_e32 v55, 1.0, v55
	v_rcp_f32_e32 v54, v54
	v_rcp_f32_e32 v55, v55
	v_and_b32_e32 v65, 0xffff0000, v65
	v_mul_f32_e32 v54, v54, v68
	v_mul_f32_e32 v55, v55, v64
	v_cvt_pk_bf16_f32 v248, v54, v55
	v_add_f32_e32 v55, v56, v60
	v_mul_f32_e32 v55, 0xbfb8aa3b, v55
	v_add_f32_e32 v56, v57, v61
	v_exp_f32_e32 v55, v55
	v_mul_f32_e32 v56, 0xbfb8aa3b, v56
	v_exp_f32_e32 v56, v56
	v_add_f32_e32 v55, 1.0, v55
	v_rcp_f32_e32 v55, v55
	v_add_f32_e32 v56, 1.0, v56
	v_rcp_f32_e32 v56, v56
	v_mul_f32_e32 v55, v55, v69
	v_mul_f32_e32 v56, v56, v65
	v_cvt_pk_bf16_f32 v249, v55, v56
	s_waitcnt vmcnt(13)
	v_mov_b64_e32 v[54:55], v[152:153]
	ds_read_b128 v[56:59], v172 offset:192
	v_lshlrev_b32_e32 v60, 16, v54
	s_waitcnt lgkmcnt(0)
	v_add_f32_e32 v50, v50, v56
	v_add_f32_e32 v51, v51, v57
	v_mul_f32_e32 v50, 0xbfb8aa3b, v50
	v_mul_f32_e32 v51, 0xbfb8aa3b, v51
	v_exp_f32_e32 v50, v50
	v_exp_f32_e32 v51, v51
	v_and_b32_e32 v54, 0xffff0000, v54
	v_lshlrev_b32_e32 v61, 16, v55
	v_add_f32_e32 v50, 1.0, v50
	v_add_f32_e32 v51, 1.0, v51
	v_rcp_f32_e32 v50, v50
	v_rcp_f32_e32 v51, v51
	v_and_b32_e32 v55, 0xffff0000, v55
	v_mul_f32_e32 v50, v50, v60
	v_mul_f32_e32 v51, v51, v54
	v_cvt_pk_bf16_f32 v250, v50, v51
	v_add_f32_e32 v51, v52, v58
	v_mul_f32_e32 v51, 0xbfb8aa3b, v51
	v_add_f32_e32 v52, v53, v59
	v_exp_f32_e32 v51, v51
	v_mul_f32_e32 v52, 0xbfb8aa3b, v52
	v_exp_f32_e32 v52, v52
	v_add_f32_e32 v51, 1.0, v51
	v_rcp_f32_e32 v51, v51
	v_add_f32_e32 v52, 1.0, v52
	v_rcp_f32_e32 v52, v52
	v_mul_f32_e32 v51, v51, v61
	v_mul_f32_e32 v52, v52, v55
	v_cvt_pk_bf16_f32 v251, v51, v52
	v_lshl_add_u64 v[252:253], v[62:63], 0, v[176:177]
	s_nop 1
	v_permlane16_swap_b32_e32 v248, v250
	v_permlane16_swap_b32_e32 v249, v251
	global_store_dwordx4 v[252:253], v[248:251], off offset:64
	v_lshl_add_u64 v[50:51], s[24:25], 0, v[206:207]
	v_lshl_add_u64 v[50:51], v[50:51], 0, v[0:1]
	s_waitcnt vmcnt(12)
	v_permlane16_swap_b32_e32 v154, v156
	v_permlane16_swap_b32_e32 v155, v157
	v_mov_b64_e32 v[56:57], v[154:155]
	ds_read_b128 v[52:55], v172
	v_lshlrev_b32_e32 v58, 16, v56
	s_waitcnt lgkmcnt(0)
	v_add_f32_e32 v46, v46, v52
	v_add_f32_e32 v47, v47, v53
	v_mul_f32_e32 v46, 0xbfb8aa3b, v46
	v_mul_f32_e32 v47, 0xbfb8aa3b, v47
	v_exp_f32_e32 v46, v46
	v_exp_f32_e32 v47, v47
	v_and_b32_e32 v56, 0xffff0000, v56
	v_lshlrev_b32_e32 v59, 16, v57
	v_add_f32_e32 v46, 1.0, v46
	v_add_f32_e32 v47, 1.0, v47
	v_rcp_f32_e32 v46, v46
	v_rcp_f32_e32 v47, v47
	v_and_b32_e32 v57, 0xffff0000, v57
	v_mul_f32_e32 v46, v46, v58
	v_mul_f32_e32 v47, v47, v56
	v_cvt_pk_bf16_f32 v248, v46, v47
	v_add_f32_e32 v46, v48, v54
	v_add_f32_e32 v47, v49, v55
	v_mul_f32_e32 v46, 0xbfb8aa3b, v46
	v_mul_f32_e32 v47, 0xbfb8aa3b, v47
	v_exp_f32_e32 v46, v46
	v_exp_f32_e32 v47, v47
	v_add_f32_e32 v46, 1.0, v46
	v_add_f32_e32 v47, 1.0, v47
	v_rcp_f32_e32 v46, v46
	v_rcp_f32_e32 v47, v47
	v_mul_f32_e32 v46, v46, v59
	v_mul_f32_e32 v47, v47, v57
	v_cvt_pk_bf16_f32 v249, v46, v47
	v_lshl_add_u64 v[46:47], s[22:23], 0, v[206:207]
	v_lshl_add_u64 v[46:47], v[46:47], 0, v[0:1]
	s_waitcnt vmcnt(12)
	v_mov_b64_e32 v[48:49], v[156:157]
	ds_read_b128 v[52:55], v172 offset:64
	v_lshlrev_b32_e32 v56, 16, v48
	s_waitcnt lgkmcnt(0)
	v_add_f32_e32 v42, v42, v52
	v_add_f32_e32 v43, v43, v53
	v_mul_f32_e32 v42, 0xbfb8aa3b, v42
	v_mul_f32_e32 v43, 0xbfb8aa3b, v43
	v_exp_f32_e32 v42, v42
	v_exp_f32_e32 v43, v43
	v_and_b32_e32 v48, 0xffff0000, v48
	v_lshlrev_b32_e32 v57, 16, v49
	v_add_f32_e32 v42, 1.0, v42
	v_add_f32_e32 v43, 1.0, v43
	v_rcp_f32_e32 v42, v42
	v_rcp_f32_e32 v43, v43
	v_and_b32_e32 v49, 0xffff0000, v49
	v_mul_f32_e32 v42, v42, v56
	v_mul_f32_e32 v43, v43, v48
	v_cvt_pk_bf16_f32 v250, v42, v43
	v_add_f32_e32 v43, v44, v54
	v_mul_f32_e32 v43, 0xbfb8aa3b, v43
	v_add_f32_e32 v44, v45, v55
	v_exp_f32_e32 v43, v43
	v_mul_f32_e32 v44, 0xbfb8aa3b, v44
	v_exp_f32_e32 v44, v44
	v_add_f32_e32 v43, 1.0, v43
	v_rcp_f32_e32 v43, v43
	v_add_f32_e32 v44, 1.0, v44
	v_rcp_f32_e32 v44, v44
	v_mul_f32_e32 v43, v43, v57
	v_mul_f32_e32 v44, v44, v49
	v_cvt_pk_bf16_f32 v251, v43, v44
	v_lshl_add_u64 v[252:253], v[46:47], 0, v[176:177]
	s_nop 1
	v_permlane16_swap_b32_e32 v248, v250
	v_permlane16_swap_b32_e32 v249, v251
	global_store_dwordx4 v[252:253], v[248:251], off
	s_waitcnt vmcnt(11)
	v_permlane16_swap_b32_e32 v158, v160
	v_permlane16_swap_b32_e32 v159, v161
	v_mov_b64_e32 v[48:49], v[158:159]
	ds_read_b128 v[42:45], v172 offset:128
	v_lshlrev_b32_e32 v52, 16, v48
	s_waitcnt lgkmcnt(0)
	v_add_f32_e32 v38, v38, v42
	v_add_f32_e32 v39, v39, v43
	v_mul_f32_e32 v38, 0xbfb8aa3b, v38
	v_mul_f32_e32 v39, 0xbfb8aa3b, v39
	v_exp_f32_e32 v38, v38
	v_exp_f32_e32 v39, v39
	v_and_b32_e32 v48, 0xffff0000, v48
	v_lshlrev_b32_e32 v53, 16, v49
	v_add_f32_e32 v38, 1.0, v38
	v_add_f32_e32 v39, 1.0, v39
	v_rcp_f32_e32 v38, v38
	v_rcp_f32_e32 v39, v39
	v_and_b32_e32 v49, 0xffff0000, v49
	v_mul_f32_e32 v38, v38, v52
	v_mul_f32_e32 v39, v39, v48
	v_cvt_pk_bf16_f32 v248, v38, v39
	v_add_f32_e32 v39, v40, v44
	v_mul_f32_e32 v39, 0xbfb8aa3b, v39
	v_add_f32_e32 v40, v41, v45
	v_exp_f32_e32 v39, v39
	v_mul_f32_e32 v40, 0xbfb8aa3b, v40
	v_exp_f32_e32 v40, v40
	v_add_f32_e32 v39, 1.0, v39
	v_rcp_f32_e32 v39, v39
	v_add_f32_e32 v40, 1.0, v40
	v_rcp_f32_e32 v40, v40
	v_mul_f32_e32 v39, v39, v53
	v_mul_f32_e32 v40, v40, v49
	v_cvt_pk_bf16_f32 v249, v39, v40
	s_waitcnt vmcnt(11)
	v_mov_b64_e32 v[38:39], v[160:161]
	ds_read_b128 v[40:43], v172 offset:192
	v_lshlrev_b32_e32 v44, 16, v38
	s_waitcnt lgkmcnt(0)
	v_add_f32_e32 v34, v34, v40
	v_add_f32_e32 v35, v35, v41
	v_mul_f32_e32 v34, 0xbfb8aa3b, v34
	v_mul_f32_e32 v35, 0xbfb8aa3b, v35
	v_exp_f32_e32 v34, v34
	v_exp_f32_e32 v35, v35
	v_and_b32_e32 v38, 0xffff0000, v38
	v_lshlrev_b32_e32 v45, 16, v39
	v_add_f32_e32 v34, 1.0, v34
	v_add_f32_e32 v35, 1.0, v35
	v_rcp_f32_e32 v34, v34
	v_rcp_f32_e32 v35, v35
	v_and_b32_e32 v39, 0xffff0000, v39
	v_mul_f32_e32 v34, v34, v44
	v_mul_f32_e32 v35, v35, v38
	v_cvt_pk_bf16_f32 v250, v34, v35
	v_add_f32_e32 v35, v36, v42
	v_mul_f32_e32 v35, 0xbfb8aa3b, v35
	v_add_f32_e32 v36, v37, v43
	v_exp_f32_e32 v35, v35
	v_mul_f32_e32 v36, 0xbfb8aa3b, v36
	v_exp_f32_e32 v36, v36
	v_add_f32_e32 v35, 1.0, v35
	v_rcp_f32_e32 v35, v35
	v_add_f32_e32 v36, 1.0, v36
	v_rcp_f32_e32 v36, v36
	v_mul_f32_e32 v35, v35, v45
	v_mul_f32_e32 v36, v36, v39
	v_cvt_pk_bf16_f32 v251, v35, v36
	v_lshl_add_u64 v[252:253], v[46:47], 0, v[176:177]
	s_nop 1
	v_permlane16_swap_b32_e32 v248, v250
	v_permlane16_swap_b32_e32 v249, v251
	global_store_dwordx4 v[252:253], v[248:251], off offset:64
	v_lshl_add_u64 v[34:35], s[24:25], 0, v[208:209]
	v_lshl_add_u64 v[34:35], v[34:35], 0, v[0:1]
	s_waitcnt vmcnt(10)
	v_permlane16_swap_b32_e32 v162, v164
	v_permlane16_swap_b32_e32 v163, v165
	v_mov_b64_e32 v[40:41], v[162:163]
	ds_read_b128 v[36:39], v172
	v_lshlrev_b32_e32 v42, 16, v40
	s_waitcnt lgkmcnt(0)
	v_add_f32_e32 v30, v30, v36
	v_add_f32_e32 v31, v31, v37
	v_mul_f32_e32 v30, 0xbfb8aa3b, v30
	v_mul_f32_e32 v31, 0xbfb8aa3b, v31
	v_exp_f32_e32 v30, v30
	v_exp_f32_e32 v31, v31
	v_and_b32_e32 v40, 0xffff0000, v40
	v_lshlrev_b32_e32 v43, 16, v41
	v_add_f32_e32 v30, 1.0, v30
	v_add_f32_e32 v31, 1.0, v31
	v_rcp_f32_e32 v30, v30
	v_rcp_f32_e32 v31, v31
	v_and_b32_e32 v41, 0xffff0000, v41
	v_mul_f32_e32 v30, v30, v42
	v_mul_f32_e32 v31, v31, v40
	v_cvt_pk_bf16_f32 v248, v30, v31
	v_add_f32_e32 v30, v32, v38
	v_add_f32_e32 v31, v33, v39
	v_mul_f32_e32 v30, 0xbfb8aa3b, v30
	v_mul_f32_e32 v31, 0xbfb8aa3b, v31
	v_exp_f32_e32 v30, v30
	v_exp_f32_e32 v31, v31
	v_add_f32_e32 v30, 1.0, v30
	v_add_f32_e32 v31, 1.0, v31
	v_rcp_f32_e32 v30, v30
	v_rcp_f32_e32 v31, v31
	v_mul_f32_e32 v30, v30, v43
	v_mul_f32_e32 v31, v31, v41
	v_cvt_pk_bf16_f32 v249, v30, v31
	v_lshl_add_u64 v[30:31], s[22:23], 0, v[208:209]
	v_lshl_add_u64 v[30:31], v[30:31], 0, v[0:1]
	s_waitcnt vmcnt(10)
	v_mov_b64_e32 v[32:33], v[164:165]
	ds_read_b128 v[36:39], v172 offset:64
	v_lshlrev_b32_e32 v40, 16, v32
	s_waitcnt lgkmcnt(0)
	v_add_f32_e32 v26, v26, v36
	v_add_f32_e32 v27, v27, v37
	v_mul_f32_e32 v26, 0xbfb8aa3b, v26
	v_mul_f32_e32 v27, 0xbfb8aa3b, v27
	v_exp_f32_e32 v26, v26
	v_exp_f32_e32 v27, v27
	v_and_b32_e32 v32, 0xffff0000, v32
	v_lshlrev_b32_e32 v41, 16, v33
	v_add_f32_e32 v26, 1.0, v26
	v_add_f32_e32 v27, 1.0, v27
	v_rcp_f32_e32 v26, v26
	v_rcp_f32_e32 v27, v27
	v_and_b32_e32 v33, 0xffff0000, v33
	v_mul_f32_e32 v26, v26, v40
	v_mul_f32_e32 v27, v27, v32
	v_cvt_pk_bf16_f32 v250, v26, v27
	v_add_f32_e32 v27, v28, v38
	v_mul_f32_e32 v27, 0xbfb8aa3b, v27
	v_add_f32_e32 v28, v29, v39
	v_exp_f32_e32 v27, v27
	v_mul_f32_e32 v28, 0xbfb8aa3b, v28
	v_exp_f32_e32 v28, v28
	v_add_f32_e32 v27, 1.0, v27
	v_rcp_f32_e32 v27, v27
	v_add_f32_e32 v28, 1.0, v28
	v_rcp_f32_e32 v28, v28
	v_mul_f32_e32 v27, v27, v41
	v_mul_f32_e32 v28, v28, v33
	v_cvt_pk_bf16_f32 v251, v27, v28
	v_lshl_add_u64 v[252:253], v[30:31], 0, v[176:177]
	s_nop 1
	v_permlane16_swap_b32_e32 v248, v250
	v_permlane16_swap_b32_e32 v249, v251
	global_store_dwordx4 v[252:253], v[248:251], off
	s_waitcnt vmcnt(9)
	v_permlane16_swap_b32_e32 v166, v168
	v_permlane16_swap_b32_e32 v167, v169
	v_mov_b64_e32 v[32:33], v[166:167]
	ds_read_b128 v[26:29], v172 offset:128
	v_lshlrev_b32_e32 v36, 16, v32
	s_waitcnt lgkmcnt(0)
	v_add_f32_e32 v22, v22, v26
	v_add_f32_e32 v23, v23, v27
	v_mul_f32_e32 v22, 0xbfb8aa3b, v22
	v_mul_f32_e32 v23, 0xbfb8aa3b, v23
	v_exp_f32_e32 v22, v22
	v_exp_f32_e32 v23, v23
	v_and_b32_e32 v32, 0xffff0000, v32
	v_lshlrev_b32_e32 v37, 16, v33
	v_add_f32_e32 v22, 1.0, v22
	v_add_f32_e32 v23, 1.0, v23
	v_rcp_f32_e32 v22, v22
	v_rcp_f32_e32 v23, v23
	v_and_b32_e32 v33, 0xffff0000, v33
	v_mul_f32_e32 v22, v22, v36
	v_mul_f32_e32 v23, v23, v32
	v_cvt_pk_bf16_f32 v248, v22, v23
	v_add_f32_e32 v23, v24, v28
	v_mul_f32_e32 v23, 0xbfb8aa3b, v23
	v_add_f32_e32 v24, v25, v29
	v_exp_f32_e32 v23, v23
	v_mul_f32_e32 v24, 0xbfb8aa3b, v24
	v_exp_f32_e32 v24, v24
	v_add_f32_e32 v23, 1.0, v23
	v_rcp_f32_e32 v23, v23
	v_add_f32_e32 v24, 1.0, v24
	v_rcp_f32_e32 v24, v24
	v_mul_f32_e32 v23, v23, v37
	v_mul_f32_e32 v24, v24, v33
	v_cvt_pk_bf16_f32 v249, v23, v24
	s_waitcnt vmcnt(9)
	v_mov_b64_e32 v[22:23], v[168:169]
	ds_read_b128 v[24:27], v172 offset:192
	v_lshlrev_b32_e32 v28, 16, v22
	s_waitcnt lgkmcnt(0)
	v_add_f32_e32 v18, v18, v24
	v_add_f32_e32 v19, v19, v25
	v_mul_f32_e32 v18, 0xbfb8aa3b, v18
	v_mul_f32_e32 v19, 0xbfb8aa3b, v19
	v_exp_f32_e32 v18, v18
	v_exp_f32_e32 v19, v19
	v_and_b32_e32 v22, 0xffff0000, v22
	v_lshlrev_b32_e32 v29, 16, v23
	v_add_f32_e32 v18, 1.0, v18
	v_add_f32_e32 v19, 1.0, v19
	v_rcp_f32_e32 v18, v18
	v_rcp_f32_e32 v19, v19
	v_and_b32_e32 v23, 0xffff0000, v23
	v_mul_f32_e32 v18, v18, v28
	v_mul_f32_e32 v19, v19, v22
	v_cvt_pk_bf16_f32 v250, v18, v19
	v_add_f32_e32 v19, v20, v26
	v_mul_f32_e32 v19, 0xbfb8aa3b, v19
	v_add_f32_e32 v20, v21, v27
	v_exp_f32_e32 v19, v19
	v_mul_f32_e32 v20, 0xbfb8aa3b, v20
	v_exp_f32_e32 v20, v20
	v_add_f32_e32 v19, 1.0, v19
	v_rcp_f32_e32 v19, v19
	v_add_f32_e32 v20, 1.0, v20
	v_rcp_f32_e32 v20, v20
	v_mul_f32_e32 v19, v19, v29
	v_mul_f32_e32 v20, v20, v23
	v_cvt_pk_bf16_f32 v251, v19, v20
	v_lshl_add_u64 v[252:253], v[30:31], 0, v[176:177]
	s_nop 1
	v_permlane16_swap_b32_e32 v248, v250
	v_permlane16_swap_b32_e32 v249, v251
	global_store_dwordx4 v[252:253], v[248:251], off offset:64
	v_lshl_add_u64 v[18:19], s[24:25], 0, v[210:211]
	v_lshl_add_u64 v[18:19], v[18:19], 0, v[0:1]
	s_waitcnt vmcnt(8)
	v_permlane16_swap_b32_e32 v142, v144
	v_permlane16_swap_b32_e32 v143, v145
	v_mov_b64_e32 v[24:25], v[142:143]
	ds_read_b128 v[20:23], v172
	v_lshlrev_b32_e32 v26, 16, v24
	s_waitcnt lgkmcnt(0)
	v_add_f32_e32 v14, v14, v20
	v_add_f32_e32 v15, v15, v21
	v_mul_f32_e32 v14, 0xbfb8aa3b, v14
	v_mul_f32_e32 v15, 0xbfb8aa3b, v15
	v_exp_f32_e32 v14, v14
	v_exp_f32_e32 v15, v15
	v_and_b32_e32 v24, 0xffff0000, v24
	v_lshlrev_b32_e32 v27, 16, v25
	v_add_f32_e32 v14, 1.0, v14
	v_add_f32_e32 v15, 1.0, v15
	v_rcp_f32_e32 v14, v14
	v_rcp_f32_e32 v15, v15
	v_and_b32_e32 v25, 0xffff0000, v25
	v_mul_f32_e32 v14, v14, v26
	v_mul_f32_e32 v15, v15, v24
	v_cvt_pk_bf16_f32 v248, v14, v15
	v_add_f32_e32 v14, v16, v22
	v_add_f32_e32 v15, v17, v23
	v_mul_f32_e32 v14, 0xbfb8aa3b, v14
	v_mul_f32_e32 v15, 0xbfb8aa3b, v15
	v_exp_f32_e32 v14, v14
	v_exp_f32_e32 v15, v15
	v_add_f32_e32 v14, 1.0, v14
	v_add_f32_e32 v15, 1.0, v15
	v_rcp_f32_e32 v14, v14
	v_rcp_f32_e32 v15, v15
	v_mul_f32_e32 v14, v14, v27
	v_mul_f32_e32 v15, v15, v25
	v_cvt_pk_bf16_f32 v249, v14, v15
	v_lshl_add_u64 v[14:15], s[22:23], 0, v[210:211]
	v_lshl_add_u64 v[14:15], v[14:15], 0, v[0:1]
	s_waitcnt vmcnt(8)
	v_mov_b64_e32 v[16:17], v[144:145]
	ds_read_b128 v[20:23], v172 offset:64
	v_lshlrev_b32_e32 v0, 16, v16
	s_waitcnt lgkmcnt(0)
	v_add_f32_e32 v10, v10, v20
	v_mul_f32_e32 v10, 0xbfb8aa3b, v10
	v_exp_f32_e32 v10, v10
	v_and_b32_e32 v16, 0xffff0000, v16
	v_lshlrev_b32_e32 v24, 16, v17
	v_and_b32_e32 v17, 0xffff0000, v17
	v_add_f32_e32 v10, 1.0, v10
	v_rcp_f32_e32 v10, v10
	s_nop 0
	v_mul_f32_e32 v0, v10, v0
	v_add_f32_e32 v10, v11, v21
	v_mul_f32_e32 v10, 0xbfb8aa3b, v10
	v_exp_f32_e32 v10, v10
	v_add_f32_e32 v11, v13, v23
	v_mul_f32_e32 v11, 0xbfb8aa3b, v11
	v_exp_f32_e32 v11, v11
	v_add_f32_e32 v10, 1.0, v10
	v_rcp_f32_e32 v10, v10
	v_add_f32_e32 v11, 1.0, v11
	v_rcp_f32_e32 v11, v11
	v_mul_f32_e32 v10, v10, v16
	v_cvt_pk_bf16_f32 v250, v0, v10
	v_add_f32_e32 v0, v12, v22
	v_mul_f32_e32 v0, 0xbfb8aa3b, v0
	v_exp_f32_e32 v0, v0
	v_mul_f32_e32 v11, v11, v17
	v_add_f32_e32 v0, 1.0, v0
	v_rcp_f32_e32 v0, v0
	s_nop 0
	v_mul_f32_e32 v0, v0, v24
	v_cvt_pk_bf16_f32 v251, v0, v11
	v_lshl_add_u64 v[252:253], v[14:15], 0, v[176:177]
	s_nop 1
	v_permlane16_swap_b32_e32 v248, v250
	v_permlane16_swap_b32_e32 v249, v251
	global_store_dwordx4 v[252:253], v[248:251], off
	s_waitcnt vmcnt(7)
	v_permlane16_swap_b32_e32 v146, v148
	v_permlane16_swap_b32_e32 v147, v149
	v_mov_b64_e32 v[16:17], v[146:147]
	ds_read_b128 v[10:13], v172 offset:128
	v_lshlrev_b32_e32 v0, 16, v16
	s_waitcnt lgkmcnt(0)
	v_add_f32_e32 v6, v6, v10
	v_mul_f32_e32 v6, 0xbfb8aa3b, v6
	v_exp_f32_e32 v6, v6
	v_and_b32_e32 v16, 0xffff0000, v16
	v_lshlrev_b32_e32 v20, 16, v17
	v_and_b32_e32 v17, 0xffff0000, v17
	v_add_f32_e32 v6, 1.0, v6
	v_rcp_f32_e32 v6, v6
	s_nop 0
	v_mul_f32_e32 v0, v6, v0
	v_add_f32_e32 v6, v7, v11
	v_mul_f32_e32 v6, 0xbfb8aa3b, v6
	v_exp_f32_e32 v6, v6
	v_add_f32_e32 v7, v9, v13
	v_mul_f32_e32 v7, 0xbfb8aa3b, v7
	v_exp_f32_e32 v7, v7
	v_add_f32_e32 v6, 1.0, v6
	v_rcp_f32_e32 v6, v6
	v_add_f32_e32 v7, 1.0, v7
	v_rcp_f32_e32 v7, v7
	v_mul_f32_e32 v6, v6, v16
	v_cvt_pk_bf16_f32 v248, v0, v6
	v_add_f32_e32 v0, v8, v12
	v_mul_f32_e32 v0, 0xbfb8aa3b, v0
	v_exp_f32_e32 v0, v0
	v_mul_f32_e32 v7, v7, v17
	v_add_f32_e32 v0, 1.0, v0
	v_rcp_f32_e32 v0, v0
	s_nop 0
	v_mul_f32_e32 v0, v0, v20
	v_cvt_pk_bf16_f32 v249, v0, v7
	s_waitcnt vmcnt(7)
	v_mov_b64_e32 v[6:7], v[148:149]
	ds_read_b128 v[8:11], v172 offset:192
	v_lshlrev_b32_e32 v0, 16, v6
	s_waitcnt lgkmcnt(0)
	v_add_f32_e32 v2, v2, v8
	v_mul_f32_e32 v2, 0xbfb8aa3b, v2
	v_exp_f32_e32 v2, v2
	v_and_b32_e32 v6, 0xffff0000, v6
	v_lshlrev_b32_e32 v12, 16, v7
	v_and_b32_e32 v7, 0xffff0000, v7
	v_add_f32_e32 v2, 1.0, v2
	v_rcp_f32_e32 v2, v2
	s_nop 0
	v_mul_f32_e32 v0, v2, v0
	v_add_f32_e32 v2, v3, v9
	v_mul_f32_e32 v2, 0xbfb8aa3b, v2
	v_exp_f32_e32 v2, v2
	v_add_f32_e32 v3, v5, v11
	v_mul_f32_e32 v3, 0xbfb8aa3b, v3
	v_exp_f32_e32 v3, v3
	v_add_f32_e32 v2, 1.0, v2
	v_rcp_f32_e32 v2, v2
	v_add_f32_e32 v3, 1.0, v3
	v_rcp_f32_e32 v3, v3
	v_mul_f32_e32 v2, v2, v6
	v_cvt_pk_bf16_f32 v250, v0, v2
	v_add_f32_e32 v0, v4, v10
	v_mul_f32_e32 v0, 0xbfb8aa3b, v0
	v_exp_f32_e32 v0, v0
	v_mul_f32_e32 v3, v3, v7
	v_add_f32_e32 v0, 1.0, v0
	v_rcp_f32_e32 v0, v0
	s_nop 0
	v_mul_f32_e32 v0, v0, v12
	v_cvt_pk_bf16_f32 v251, v0, v3
	v_lshl_add_u64 v[252:253], v[14:15], 0, v[176:177]
	s_nop 1
	v_permlane16_swap_b32_e32 v248, v250
	v_permlane16_swap_b32_e32 v249, v251
	global_store_dwordx4 v[252:253], v[248:251], off offset:64
	s_andn2_b64 vcc, exec, s[18:19]
	s_mov_b64 s[18:19], -1
	s_cbranch_vccnz .LBB0_1384
	s_mov_b64 s[18:19], 0
	s_branch .LBB0_1384
